# v11 + ALIGN_EPI leading-half barrier moved 48 instructions into the FFN-up epilogues (leading half works during the trailing half's last MFMA block)
# baseline (speedup 1.0000x reference)
.LBB0_159:
	v_exp_f32_e64 v140, -v122
	v_exp_f32_e64 v141, -v123
	v_pk_mul_f32 v[128:129], v[124:125], v[128:129]
	v_exp_f32_e64 v124, -v124
	v_exp_f32_e64 v125, -v125
	v_pk_add_f32 v[140:141], v[140:141], 1.0 op_sel_hi:[1,0]
	v_pk_mul_f32 v[122:123], v[122:123], v[126:127]
	v_rcp_f32_e32 v126, v140
	v_rcp_f32_e32 v127, v141
	v_pk_add_f32 v[124:125], v[124:125], 1.0 op_sel_hi:[1,0]
	v_lshl_or_b32 v142, s86, 7, v136
	v_rcp_f32_e32 v124, v124
	v_rcp_f32_e32 v125, v125
	v_pk_mul_f32 v[122:123], v[126:127], v[122:123]
	v_exp_f32_e64 v126, -v114
	v_exp_f32_e64 v127, -v115
	v_pk_mul_f32 v[124:125], v[124:125], v[128:129]
	v_exp_f32_e64 v128, -v116
	v_exp_f32_e64 v129, -v117
	v_pk_add_f32 v[126:127], v[126:127], 1.0 op_sel_hi:[1,0]
	v_pk_mul_f32 v[114:115], v[114:115], v[118:119]
	v_rcp_f32_e32 v126, v126
	v_rcp_f32_e32 v127, v127
	v_pk_add_f32 v[128:129], v[128:129], 1.0 op_sel_hi:[1,0]
	v_pk_mul_f32 v[116:117], v[116:117], v[120:121]
	v_rcp_f32_e32 v128, v128
	v_rcp_f32_e32 v129, v129
	v_pk_mul_f32 v[114:115], v[126:127], v[114:115]
	v_cvt_pk_bf16_f32 v118, v122, v123
	v_cvt_pk_bf16_f32 v119, v124, v125
	v_exp_f32_e64 v124, -v106
	v_exp_f32_e64 v125, -v107
	v_lshl_add_u32 v139, s50, 8, v135
	v_ashrrev_i32_e32 v143, 31, v142
	v_pk_mul_f32 v[116:117], v[128:129], v[116:117]
	v_cvt_pk_bf16_f32 v120, v114, v115
	v_mov_b64_e32 v[114:115], s[18:19]
	v_pk_mul_f32 v[112:113], v[108:109], v[112:113]
	v_exp_f32_e64 v108, -v108
	v_exp_f32_e64 v109, -v109
	v_cvt_pk_bf16_f32 v121, v116, v117
	v_mad_i64_i32 v[122:123], s[0:1], v139, s85, v[114:115]
	v_lshlrev_b64 v[116:117], 1, v[142:143]
	v_lshl_add_u64 v[122:123], v[122:123], 0, v[116:117]
	global_store_dwordx4 v[122:123], v[118:121], off
	v_pk_mul_f32 v[106:107], v[106:107], v[110:111]
	v_pk_add_f32 v[108:109], v[108:109], 1.0 op_sel_hi:[1,0]
	v_pk_add_f32 v[118:119], v[124:125], 1.0 op_sel_hi:[1,0]
	s_and_b64 vcc, exec, s[8:9]
	s_cbranch_vccz .Lepibar_0
	s_barrier
.Lepibar_0:
	v_rcp_f32_e32 v108, v108
	v_rcp_f32_e32 v110, v118
	v_rcp_f32_e32 v111, v119
	v_rcp_f32_e32 v109, v109
	v_pk_mul_f32 v[96:97], v[92:93], v[96:97]
	v_exp_f32_e64 v92, -v92
	v_pk_mul_f32 v[106:107], v[110:111], v[106:107]
	v_exp_f32_e64 v110, -v98
	v_exp_f32_e64 v111, -v99
	v_pk_mul_f32 v[108:109], v[108:109], v[112:113]
	v_exp_f32_e64 v112, -v100
	v_exp_f32_e64 v113, -v101
	v_pk_add_f32 v[110:111], v[110:111], 1.0 op_sel_hi:[1,0]
	v_pk_mul_f32 v[98:99], v[98:99], v[102:103]
	v_rcp_f32_e32 v110, v110
	v_rcp_f32_e32 v111, v111
	v_pk_add_f32 v[112:113], v[112:113], 1.0 op_sel_hi:[1,0]
	v_pk_mul_f32 v[100:101], v[100:101], v[104:105]
	v_rcp_f32_e32 v112, v112
	v_rcp_f32_e32 v113, v113
	v_pk_mul_f32 v[102:103], v[110:111], v[98:99]
	v_cvt_pk_bf16_f32 v98, v106, v107
	v_cvt_pk_bf16_f32 v99, v108, v109
	v_pk_mul_f32 v[104:105], v[112:113], v[100:101]
	v_cvt_pk_bf16_f32 v100, v102, v103
	v_exp_f32_e64 v102, -v90
	v_exp_f32_e64 v103, -v91
	v_cvt_pk_bf16_f32 v101, v104, v105
	v_or_b32_e32 v104, 16, v139
	v_exp_f32_e64 v93, -v93
	v_mad_i64_i32 v[104:105], s[0:1], v104, s85, v[114:115]
	v_lshl_add_u64 v[104:105], v[104:105], 0, v[116:117]
	global_store_dwordx4 v[104:105], v[98:101], off
	v_pk_mul_f32 v[90:91], v[90:91], v[94:95]
	v_pk_add_f32 v[92:93], v[92:93], 1.0 op_sel_hi:[1,0]
	v_pk_add_f32 v[98:99], v[102:103], 1.0 op_sel_hi:[1,0]
	v_rcp_f32_e32 v92, v92
	v_rcp_f32_e32 v94, v98
	v_rcp_f32_e32 v95, v99
	v_rcp_f32_e32 v93, v93
	v_pk_mul_f32 v[80:81], v[76:77], v[80:81]
	v_exp_f32_e64 v76, -v76
	v_pk_mul_f32 v[90:91], v[94:95], v[90:91]
	v_exp_f32_e64 v94, -v82
	v_exp_f32_e64 v95, -v83
	v_pk_mul_f32 v[92:93], v[92:93], v[96:97]
	v_exp_f32_e64 v96, -v84
	v_exp_f32_e64 v97, -v85
	v_pk_add_f32 v[94:95], v[94:95], 1.0 op_sel_hi:[1,0]
	v_pk_mul_f32 v[82:83], v[82:83], v[86:87]
	v_rcp_f32_e32 v94, v94
	v_rcp_f32_e32 v95, v95
	v_pk_add_f32 v[96:97], v[96:97], 1.0 op_sel_hi:[1,0]
	v_pk_mul_f32 v[84:85], v[84:85], v[88:89]
	v_rcp_f32_e32 v96, v96
	v_rcp_f32_e32 v97, v97
	v_pk_mul_f32 v[86:87], v[94:95], v[82:83]
	v_exp_f32_e64 v77, -v77
	v_cvt_pk_bf16_f32 v82, v90, v91
	v_pk_mul_f32 v[88:89], v[96:97], v[84:85]
	v_cvt_pk_bf16_f32 v83, v92, v93
	v_cvt_pk_bf16_f32 v84, v86, v87
	v_exp_f32_e64 v86, -v74
	v_exp_f32_e64 v87, -v75
	v_cvt_pk_bf16_f32 v85, v88, v89
	v_or_b32_e32 v88, 32, v139
	v_mad_i64_i32 v[88:89], s[0:1], v88, s85, v[114:115]
	v_lshl_add_u64 v[88:89], v[88:89], 0, v[116:117]
	v_pk_add_f32 v[76:77], v[76:77], 1.0 op_sel_hi:[1,0]
	global_store_dwordx4 v[88:89], v[82:85], off
	v_rcp_f32_e32 v76, v76
	v_rcp_f32_e32 v77, v77
	v_pk_add_f32 v[82:83], v[86:87], 1.0 op_sel_hi:[1,0]
	v_pk_mul_f32 v[74:75], v[74:75], v[78:79]
	v_rcp_f32_e32 v78, v82
	v_rcp_f32_e32 v79, v83
	v_pk_mul_f32 v[76:77], v[76:77], v[80:81]
	v_exp_f32_e64 v80, -v68
	v_exp_f32_e64 v81, -v69
	v_pk_mul_f32 v[74:75], v[78:79], v[74:75]
	v_exp_f32_e64 v78, -v66
	v_exp_f32_e64 v79, -v67
	v_pk_add_f32 v[80:81], v[80:81], 1.0 op_sel_hi:[1,0]
	v_pk_mul_f32 v[68:69], v[68:69], v[72:73]
	v_rcp_f32_e32 v80, v80
	v_pk_add_f32 v[78:79], v[78:79], 1.0 op_sel_hi:[1,0]
	v_rcp_f32_e32 v81, v81
	v_rcp_f32_e32 v78, v78
	v_rcp_f32_e32 v79, v79
	v_pk_mul_f32 v[66:67], v[66:67], v[70:71]
	v_pk_mul_f32 v[72:73], v[80:81], v[68:69]
	v_pk_mul_f32 v[64:65], v[60:61], v[64:65]
	v_pk_mul_f32 v[70:71], v[78:79], v[66:67]
	v_cvt_pk_bf16_f32 v66, v74, v75
	v_cvt_pk_bf16_f32 v67, v76, v77
	v_exp_f32_e64 v60, -v60
	v_cvt_pk_bf16_f32 v68, v70, v71
	v_cvt_pk_bf16_f32 v69, v72, v73
	v_exp_f32_e64 v72, -v58
	v_exp_f32_e64 v73, -v59
	v_or_b32_e32 v70, 48, v139
	v_exp_f32_e64 v61, -v61
	v_mad_i64_i32 v[70:71], s[0:1], v70, s85, v[114:115]
	v_lshl_add_u64 v[70:71], v[70:71], 0, v[116:117]
	global_store_dwordx4 v[70:71], v[66:69], off
	v_pk_mul_f32 v[58:59], v[58:59], v[62:63]
	v_pk_add_f32 v[60:61], v[60:61], 1.0 op_sel_hi:[1,0]
	v_pk_add_f32 v[66:67], v[72:73], 1.0 op_sel_hi:[1,0]
	v_rcp_f32_e32 v60, v60
	v_rcp_f32_e32 v62, v66
	v_rcp_f32_e32 v63, v67
	v_rcp_f32_e32 v61, v61
	v_add_u32_e32 v68, 0x80, v139
	v_pk_mul_f32 v[48:49], v[44:45], v[48:49]
	v_pk_mul_f32 v[58:59], v[62:63], v[58:59]
	v_exp_f32_e64 v62, -v50
	v_exp_f32_e64 v63, -v51
	v_pk_mul_f32 v[60:61], v[60:61], v[64:65]
	v_exp_f32_e64 v64, -v52
	v_exp_f32_e64 v65, -v53
	v_pk_add_f32 v[62:63], v[62:63], 1.0 op_sel_hi:[1,0]
	v_pk_mul_f32 v[50:51], v[50:51], v[54:55]
	v_rcp_f32_e32 v62, v62
	v_rcp_f32_e32 v63, v63
	v_pk_add_f32 v[64:65], v[64:65], 1.0 op_sel_hi:[1,0]
	v_pk_mul_f32 v[52:53], v[52:53], v[56:57]
	v_rcp_f32_e32 v64, v64
	v_rcp_f32_e32 v65, v65
	v_pk_mul_f32 v[54:55], v[62:63], v[50:51]
	v_cvt_pk_bf16_f32 v50, v58, v59
	v_cvt_pk_bf16_f32 v51, v60, v61
	v_pk_mul_f32 v[56:57], v[64:65], v[52:53]
	v_cvt_pk_bf16_f32 v52, v54, v55
	v_exp_f32_e64 v54, -v42
	v_exp_f32_e64 v55, -v43
	v_exp_f32_e64 v44, -v44
	v_exp_f32_e64 v45, -v45
	v_cvt_pk_bf16_f32 v53, v56, v57
	v_mad_i64_i32 v[56:57], s[0:1], v68, s85, v[114:115]
	v_lshl_add_u64 v[56:57], v[56:57], 0, v[116:117]
	global_store_dwordx4 v[56:57], v[50:53], off
	v_pk_mul_f32 v[42:43], v[42:43], v[46:47]
	v_pk_add_f32 v[44:45], v[44:45], 1.0 op_sel_hi:[1,0]
	v_pk_add_f32 v[50:51], v[54:55], 1.0 op_sel_hi:[1,0]
	v_rcp_f32_e32 v44, v44
	v_rcp_f32_e32 v46, v50
	v_rcp_f32_e32 v47, v51
	v_rcp_f32_e32 v45, v45
	v_pk_mul_f32 v[32:33], v[28:29], v[32:33]
	v_exp_f32_e64 v28, -v28
	v_pk_mul_f32 v[42:43], v[46:47], v[42:43]
	v_exp_f32_e64 v46, -v34
	v_exp_f32_e64 v47, -v35
	v_pk_mul_f32 v[44:45], v[44:45], v[48:49]
	v_exp_f32_e64 v48, -v36
	v_exp_f32_e64 v49, -v37
	v_pk_add_f32 v[46:47], v[46:47], 1.0 op_sel_hi:[1,0]
	v_pk_mul_f32 v[34:35], v[34:35], v[38:39]
	v_rcp_f32_e32 v46, v46
	v_rcp_f32_e32 v47, v47
	v_pk_add_f32 v[48:49], v[48:49], 1.0 op_sel_hi:[1,0]
	v_pk_mul_f32 v[36:37], v[36:37], v[40:41]
	v_rcp_f32_e32 v48, v48
	v_rcp_f32_e32 v49, v49
	v_pk_mul_f32 v[38:39], v[46:47], v[34:35]
	v_cvt_pk_bf16_f32 v34, v42, v43
	v_cvt_pk_bf16_f32 v35, v44, v45
	v_pk_mul_f32 v[40:41], v[48:49], v[36:37]
	v_cvt_pk_bf16_f32 v36, v38, v39
	v_exp_f32_e64 v38, -v26
	v_exp_f32_e64 v39, -v27
	v_cvt_pk_bf16_f32 v37, v40, v41
	v_add_u32_e32 v40, 0x90, v139
	v_exp_f32_e64 v29, -v29
	v_mad_i64_i32 v[40:41], s[0:1], v40, s85, v[114:115]
	v_lshl_add_u64 v[40:41], v[40:41], 0, v[116:117]
	global_store_dwordx4 v[40:41], v[34:37], off
	v_pk_mul_f32 v[26:27], v[26:27], v[30:31]
	v_pk_add_f32 v[28:29], v[28:29], 1.0 op_sel_hi:[1,0]
	v_pk_add_f32 v[34:35], v[38:39], 1.0 op_sel_hi:[1,0]
	v_rcp_f32_e32 v28, v28
	v_rcp_f32_e32 v30, v34
	v_rcp_f32_e32 v31, v35
	v_rcp_f32_e32 v29, v29
	v_pk_mul_f32 v[16:17], v[12:13], v[16:17]
	v_exp_f32_e64 v12, -v12
	v_pk_mul_f32 v[26:27], v[30:31], v[26:27]
	v_exp_f32_e64 v30, -v18
	v_exp_f32_e64 v31, -v19
	v_pk_mul_f32 v[28:29], v[28:29], v[32:33]
	v_exp_f32_e64 v32, -v20
	v_exp_f32_e64 v33, -v21
	v_pk_add_f32 v[30:31], v[30:31], 1.0 op_sel_hi:[1,0]
	v_pk_mul_f32 v[18:19], v[18:19], v[22:23]
	v_rcp_f32_e32 v30, v30
	v_rcp_f32_e32 v31, v31
	v_pk_add_f32 v[32:33], v[32:33], 1.0 op_sel_hi:[1,0]
	v_pk_mul_f32 v[20:21], v[20:21], v[24:25]
	v_rcp_f32_e32 v32, v32
	v_rcp_f32_e32 v33, v33
	v_pk_mul_f32 v[22:23], v[30:31], v[18:19]
	v_cvt_pk_bf16_f32 v18, v26, v27
	v_cvt_pk_bf16_f32 v19, v28, v29
	v_pk_mul_f32 v[24:25], v[32:33], v[20:21]
	v_cvt_pk_bf16_f32 v20, v22, v23
	v_exp_f32_e64 v22, -v10
	v_exp_f32_e64 v23, -v11
	v_cvt_pk_bf16_f32 v21, v24, v25
	v_add_u32_e32 v24, 0xa0, v139
	v_exp_f32_e64 v13, -v13
	v_mad_i64_i32 v[24:25], s[0:1], v24, s85, v[114:115]
	v_lshl_add_u64 v[24:25], v[24:25], 0, v[116:117]
	global_store_dwordx4 v[24:25], v[18:21], off
	v_pk_mul_f32 v[10:11], v[10:11], v[14:15]
	v_pk_add_f32 v[12:13], v[12:13], 1.0 op_sel_hi:[1,0]
	v_pk_add_f32 v[18:19], v[22:23], 1.0 op_sel_hi:[1,0]
	v_rcp_f32_e32 v12, v12
	v_rcp_f32_e32 v14, v18
	v_rcp_f32_e32 v15, v19
	v_rcp_f32_e32 v13, v13
	s_andn2_b64 vcc, exec, s[2:3]
	v_pk_mul_f32 v[10:11], v[14:15], v[10:11]
	v_exp_f32_e64 v14, -v2
	v_exp_f32_e64 v15, -v3
	v_pk_mul_f32 v[12:13], v[12:13], v[16:17]
	v_exp_f32_e64 v16, -v4
	v_exp_f32_e64 v17, -v5
	v_pk_add_f32 v[14:15], v[14:15], 1.0 op_sel_hi:[1,0]
	v_pk_mul_f32 v[2:3], v[2:3], v[6:7]
	v_rcp_f32_e32 v14, v14
	v_rcp_f32_e32 v15, v15
	v_pk_add_f32 v[16:17], v[16:17], 1.0 op_sel_hi:[1,0]
	v_pk_mul_f32 v[4:5], v[4:5], v[8:9]
	v_rcp_f32_e32 v16, v16
	v_rcp_f32_e32 v17, v17
	v_pk_mul_f32 v[6:7], v[14:15], v[2:3]
	v_cvt_pk_bf16_f32 v2, v10, v11
	v_cvt_pk_bf16_f32 v3, v12, v13
	v_pk_mul_f32 v[8:9], v[16:17], v[4:5]
	v_cvt_pk_bf16_f32 v4, v6, v7
	v_add_u32_e32 v6, 0xb0, v139
	v_mad_i64_i32 v[6:7], s[0:1], v6, s85, v[114:115]
	v_cvt_pk_bf16_f32 v5, v8, v9
	v_lshl_add_u64 v[6:7], v[6:7], 0, v[116:117]
	s_mov_b64 s[0:1], -1
	global_store_dwordx4 v[6:7], v[2:5], off
	s_cbranch_vccnz .LBB0_152
	s_andn2_b64 vcc, exec, s[6:7]
	v_mov_b64 v[4:5], 0
	s_cbranch_vccnz .LBB0_151
	s_barrier
	s_branch .LBB0_151

.LBB0_560:
	v_exp_f32_e64 v144, -v122
	v_exp_f32_e64 v145, -v123
	v_pk_mul_f32 v[128:129], v[124:125], v[128:129]
	v_exp_f32_e64 v124, -v124
	v_exp_f32_e64 v125, -v125
	v_pk_add_f32 v[144:145], v[144:145], 1.0 op_sel_hi:[1,0]
	v_pk_mul_f32 v[122:123], v[122:123], v[126:127]
	v_rcp_f32_e32 v126, v144
	v_rcp_f32_e32 v127, v145
	v_pk_add_f32 v[124:125], v[124:125], 1.0 op_sel_hi:[1,0]
	v_pk_mul_f32 v[112:113], v[108:109], v[112:113]
	v_rcp_f32_e32 v124, v124
	v_rcp_f32_e32 v125, v125
	v_pk_mul_f32 v[122:123], v[126:127], v[122:123]
	v_exp_f32_e64 v126, -v114
	v_exp_f32_e64 v127, -v115
	v_pk_mul_f32 v[124:125], v[124:125], v[128:129]
	v_exp_f32_e64 v128, -v116
	v_exp_f32_e64 v129, -v117
	v_pk_add_f32 v[126:127], v[126:127], 1.0 op_sel_hi:[1,0]
	v_pk_mul_f32 v[114:115], v[114:115], v[118:119]
	v_rcp_f32_e32 v126, v126
	v_rcp_f32_e32 v127, v127
	v_pk_add_f32 v[128:129], v[128:129], 1.0 op_sel_hi:[1,0]
	v_pk_mul_f32 v[116:117], v[116:117], v[120:121]
	v_rcp_f32_e32 v128, v128
	v_rcp_f32_e32 v129, v129
	v_pk_mul_f32 v[114:115], v[126:127], v[114:115]
	v_med3_f32 v119, v122, s76, v141
	v_med3_f32 v120, v123, s76, v141
	v_mov_b32_e32 v118, 0
	v_pk_mul_f32 v[116:117], v[128:129], v[116:117]
	v_med3_f32 v114, v114, s76, v141
	v_med3_f32 v115, v115, s76, v141
	v_cvt_pk_fp8_f32 v118, v119, v120
	v_mov_b32_e32 v119, 0
	v_cvt_pk_fp8_f32 v119, v114, v115
	v_med3_f32 v114, v116, s76, v141
	v_med3_f32 v115, v117, s76, v141
	v_exp_f32_e64 v116, -v106
	v_exp_f32_e64 v117, -v107
	v_exp_f32_e64 v108, -v108
	v_exp_f32_e64 v109, -v109
	v_pk_mul_f32 v[106:107], v[106:107], v[110:111]
	v_pk_add_f32 v[116:117], v[116:117], 1.0 op_sel_hi:[1,0]
	v_lshl_add_u32 v142, s42, 8, v137
	v_rcp_f32_e32 v110, v116
	v_rcp_f32_e32 v111, v117
	s_and_b64 vcc, exec, s[10:11]
	s_cbranch_vccz .Lepibar_1
	s_barrier
.Lepibar_1:
	v_pk_add_f32 v[108:109], v[108:109], 1.0 op_sel_hi:[1,0]
	v_lshl_or_b32 v134, s78, 7, v138
	v_rcp_f32_e32 v108, v108
	v_rcp_f32_e32 v109, v109
	v_pk_mul_f32 v[106:107], v[110:111], v[106:107]
	v_exp_f32_e64 v110, -v98
	v_exp_f32_e64 v111, -v99
	v_pk_mul_f32 v[108:109], v[108:109], v[112:113]
	v_exp_f32_e64 v112, -v100
	v_exp_f32_e64 v113, -v101
	v_pk_add_f32 v[110:111], v[110:111], 1.0 op_sel_hi:[1,0]
	v_pk_mul_f32 v[98:99], v[98:99], v[102:103]
	v_rcp_f32_e32 v110, v110
	v_rcp_f32_e32 v111, v111
	v_pk_add_f32 v[112:113], v[112:113], 1.0 op_sel_hi:[1,0]
	v_med3_f32 v102, v106, s76, v141
	v_rcp_f32_e32 v112, v112
	v_rcp_f32_e32 v113, v113
	v_pk_mul_f32 v[98:99], v[110:111], v[98:99]
	v_med3_f32 v103, v107, s76, v141
	v_med3_f32 v106, v98, s76, v141
	v_med3_f32 v107, v99, s76, v141
	v_mov_b32_e32 v98, 0
	v_mov_b32_e32 v99, 0
	v_cvt_pk_fp8_f32 v98, v102, v103
	v_cvt_pk_fp8_f32 v99, v106, v107
	v_pk_mul_f32 v[100:101], v[100:101], v[104:105]
	v_med3_f32 v104, v108, s76, v141
	v_pk_mul_f32 v[100:101], v[112:113], v[100:101]
	v_med3_f32 v105, v109, s76, v141
	v_med3_f32 v100, v100, s76, v141
	v_med3_f32 v101, v101, s76, v141
	v_cvt_pk_fp8_f32 v98, v104, v105 op_sel:[0,0,1]
	v_cvt_pk_fp8_f32 v99, v100, v101 op_sel:[0,0,1]
	v_exp_f32_e64 v100, -v90
	v_exp_f32_e64 v101, -v91
	v_cvt_pk_fp8_f32 v119, v114, v115 op_sel:[0,0,1]
	v_mov_b64_e32 v[114:115], s[18:19]
	v_or_b32_e32 v102, 16, v142
	v_ashrrev_i32_e32 v135, 31, v134
	v_mad_i64_i32 v[102:103], s[0:1], v102, s77, v[114:115]
	v_lshl_add_u64 v[102:103], v[102:103], 0, v[134:135]
	global_store_dwordx2 v[102:103], v[98:99], off
	v_pk_add_f32 v[98:99], v[100:101], 1.0 op_sel_hi:[1,0]
	v_pk_mul_f32 v[96:97], v[92:93], v[96:97]
	v_exp_f32_e64 v92, -v92
	v_exp_f32_e64 v93, -v93
	v_pk_mul_f32 v[90:91], v[90:91], v[94:95]
	v_rcp_f32_e32 v94, v98
	v_rcp_f32_e32 v95, v99
	v_pk_add_f32 v[92:93], v[92:93], 1.0 op_sel_hi:[1,0]
	v_pk_mul_f32 v[80:81], v[76:77], v[80:81]
	v_rcp_f32_e32 v92, v92
	v_rcp_f32_e32 v93, v93
	v_pk_mul_f32 v[90:91], v[94:95], v[90:91]
	v_exp_f32_e64 v94, -v82
	v_exp_f32_e64 v95, -v83
	v_pk_mul_f32 v[92:93], v[92:93], v[96:97]
	v_exp_f32_e64 v96, -v84
	v_exp_f32_e64 v97, -v85
	v_pk_add_f32 v[94:95], v[94:95], 1.0 op_sel_hi:[1,0]
	v_pk_mul_f32 v[82:83], v[82:83], v[86:87]
	v_rcp_f32_e32 v94, v94
	v_rcp_f32_e32 v95, v95
	v_pk_add_f32 v[96:97], v[96:97], 1.0 op_sel_hi:[1,0]
	v_med3_f32 v86, v90, s76, v141
	v_rcp_f32_e32 v96, v96
	v_rcp_f32_e32 v97, v97
	v_pk_mul_f32 v[82:83], v[94:95], v[82:83]
	v_med3_f32 v87, v91, s76, v141
	v_med3_f32 v90, v82, s76, v141
	v_med3_f32 v91, v83, s76, v141
	v_mov_b32_e32 v82, 0
	v_mov_b32_e32 v83, 0
	v_cvt_pk_fp8_f32 v82, v86, v87
	v_cvt_pk_fp8_f32 v83, v90, v91
	v_pk_mul_f32 v[84:85], v[84:85], v[88:89]
	v_med3_f32 v88, v92, s76, v141
	v_pk_mul_f32 v[84:85], v[96:97], v[84:85]
	v_med3_f32 v89, v93, s76, v141
	v_med3_f32 v84, v84, s76, v141
	v_med3_f32 v85, v85, s76, v141
	v_cvt_pk_fp8_f32 v82, v88, v89 op_sel:[0,0,1]
	v_cvt_pk_fp8_f32 v83, v84, v85 op_sel:[0,0,1]
	v_exp_f32_e64 v84, -v74
	v_exp_f32_e64 v85, -v75
	v_or_b32_e32 v86, 32, v142
	v_mad_i64_i32 v[86:87], s[0:1], v86, s77, v[114:115]
	v_lshl_add_u64 v[86:87], v[86:87], 0, v[134:135]
	global_store_dwordx2 v[86:87], v[82:83], off
	v_pk_add_f32 v[82:83], v[84:85], 1.0 op_sel_hi:[1,0]
	v_exp_f32_e64 v76, -v76
	v_exp_f32_e64 v77, -v77
	v_pk_mul_f32 v[74:75], v[74:75], v[78:79]
	v_rcp_f32_e32 v78, v82
	v_rcp_f32_e32 v79, v83
	v_pk_add_f32 v[76:77], v[76:77], 1.0 op_sel_hi:[1,0]
	v_pk_mul_f32 v[64:65], v[60:61], v[64:65]
	v_rcp_f32_e32 v76, v76
	v_rcp_f32_e32 v77, v77
	v_pk_mul_f32 v[74:75], v[78:79], v[74:75]
	v_exp_f32_e64 v78, -v66
	v_exp_f32_e64 v79, -v67
	v_pk_mul_f32 v[76:77], v[76:77], v[80:81]
	v_exp_f32_e64 v80, -v68
	v_exp_f32_e64 v81, -v69
	v_pk_add_f32 v[78:79], v[78:79], 1.0 op_sel_hi:[1,0]
	v_pk_mul_f32 v[66:67], v[66:67], v[70:71]
	v_rcp_f32_e32 v78, v78
	v_rcp_f32_e32 v79, v79
	v_pk_add_f32 v[80:81], v[80:81], 1.0 op_sel_hi:[1,0]
	v_med3_f32 v70, v74, s76, v141
	v_rcp_f32_e32 v80, v80
	v_rcp_f32_e32 v81, v81
	v_pk_mul_f32 v[66:67], v[78:79], v[66:67]
	v_med3_f32 v71, v75, s76, v141
	v_med3_f32 v74, v66, s76, v141
	v_med3_f32 v75, v67, s76, v141
	v_mov_b32_e32 v66, 0
	v_mov_b32_e32 v67, 0
	v_cvt_pk_fp8_f32 v66, v70, v71
	v_cvt_pk_fp8_f32 v67, v74, v75
	v_pk_mul_f32 v[68:69], v[68:69], v[72:73]
	v_med3_f32 v72, v76, s76, v141
	v_pk_mul_f32 v[68:69], v[80:81], v[68:69]
	v_med3_f32 v73, v77, s76, v141
	v_med3_f32 v68, v68, s76, v141
	v_med3_f32 v69, v69, s76, v141
	v_cvt_pk_fp8_f32 v66, v72, v73 op_sel:[0,0,1]
	v_cvt_pk_fp8_f32 v67, v68, v69 op_sel:[0,0,1]
	v_exp_f32_e64 v70, -v58
	v_exp_f32_e64 v71, -v59
	v_or_b32_e32 v68, 48, v142
	v_mad_i64_i32 v[68:69], s[0:1], v68, s77, v[114:115]
	v_lshl_add_u64 v[68:69], v[68:69], 0, v[134:135]
	global_store_dwordx2 v[68:69], v[66:67], off
	v_pk_add_f32 v[66:67], v[70:71], 1.0 op_sel_hi:[1,0]
	v_exp_f32_e64 v60, -v60
	v_exp_f32_e64 v61, -v61
	v_pk_mul_f32 v[58:59], v[58:59], v[62:63]
	v_rcp_f32_e32 v62, v66
	v_rcp_f32_e32 v63, v67
	v_pk_add_f32 v[60:61], v[60:61], 1.0 op_sel_hi:[1,0]
	v_add_u32_e32 v68, 0x80, v142
	v_rcp_f32_e32 v60, v60
	v_rcp_f32_e32 v61, v61
	v_pk_mul_f32 v[58:59], v[62:63], v[58:59]
	v_exp_f32_e64 v62, -v50
	v_exp_f32_e64 v63, -v51
	v_pk_mul_f32 v[60:61], v[60:61], v[64:65]
	v_exp_f32_e64 v64, -v52
	v_exp_f32_e64 v65, -v53
	v_pk_add_f32 v[62:63], v[62:63], 1.0 op_sel_hi:[1,0]
	v_pk_mul_f32 v[50:51], v[50:51], v[54:55]
	v_rcp_f32_e32 v62, v62
	v_rcp_f32_e32 v63, v63
	v_pk_add_f32 v[64:65], v[64:65], 1.0 op_sel_hi:[1,0]
	v_med3_f32 v54, v58, s76, v141
	v_rcp_f32_e32 v64, v64
	v_rcp_f32_e32 v65, v65
	v_pk_mul_f32 v[50:51], v[62:63], v[50:51]
	v_med3_f32 v55, v59, s76, v141
	v_med3_f32 v58, v50, s76, v141
	v_med3_f32 v59, v51, s76, v141
	v_mov_b32_e32 v50, 0
	v_mov_b32_e32 v51, 0
	v_cvt_pk_fp8_f32 v50, v54, v55
	v_cvt_pk_fp8_f32 v51, v58, v59
	v_pk_mul_f32 v[52:53], v[52:53], v[56:57]
	v_med3_f32 v56, v60, s76, v141
	v_pk_mul_f32 v[52:53], v[64:65], v[52:53]
	v_med3_f32 v57, v61, s76, v141
	v_med3_f32 v52, v52, s76, v141
	v_med3_f32 v53, v53, s76, v141
	v_cvt_pk_fp8_f32 v50, v56, v57 op_sel:[0,0,1]
	v_cvt_pk_fp8_f32 v51, v52, v53 op_sel:[0,0,1]
	v_exp_f32_e64 v52, -v42
	v_exp_f32_e64 v53, -v43
	v_mad_i64_i32 v[54:55], s[0:1], v68, s77, v[114:115]
	v_lshl_add_u64 v[54:55], v[54:55], 0, v[134:135]
	global_store_dwordx2 v[54:55], v[50:51], off
	v_pk_add_f32 v[50:51], v[52:53], 1.0 op_sel_hi:[1,0]
	v_pk_mul_f32 v[48:49], v[44:45], v[48:49]
	v_exp_f32_e64 v44, -v44
	v_exp_f32_e64 v45, -v45
	v_pk_mul_f32 v[42:43], v[42:43], v[46:47]
	v_rcp_f32_e32 v46, v50
	v_rcp_f32_e32 v47, v51
	v_pk_add_f32 v[44:45], v[44:45], 1.0 op_sel_hi:[1,0]
	v_pk_mul_f32 v[32:33], v[28:29], v[32:33]
	v_rcp_f32_e32 v44, v44
	v_rcp_f32_e32 v45, v45
	v_pk_mul_f32 v[42:43], v[46:47], v[42:43]
	v_exp_f32_e64 v46, -v34
	v_exp_f32_e64 v47, -v35
	v_pk_mul_f32 v[44:45], v[44:45], v[48:49]
	v_exp_f32_e64 v48, -v36
	v_exp_f32_e64 v49, -v37
	v_pk_add_f32 v[46:47], v[46:47], 1.0 op_sel_hi:[1,0]
	v_pk_mul_f32 v[34:35], v[34:35], v[38:39]
	v_rcp_f32_e32 v46, v46
	v_rcp_f32_e32 v47, v47
	v_pk_add_f32 v[48:49], v[48:49], 1.0 op_sel_hi:[1,0]
	v_med3_f32 v38, v42, s76, v141
	v_rcp_f32_e32 v48, v48
	v_rcp_f32_e32 v49, v49
	v_pk_mul_f32 v[34:35], v[46:47], v[34:35]
	v_med3_f32 v39, v43, s76, v141
	v_med3_f32 v42, v34, s76, v141
	v_med3_f32 v43, v35, s76, v141
	v_mov_b32_e32 v34, 0
	v_mov_b32_e32 v35, 0
	v_cvt_pk_fp8_f32 v34, v38, v39
	v_cvt_pk_fp8_f32 v35, v42, v43
	v_pk_mul_f32 v[36:37], v[36:37], v[40:41]
	v_med3_f32 v40, v44, s76, v141
	v_pk_mul_f32 v[36:37], v[48:49], v[36:37]
	v_med3_f32 v41, v45, s76, v141
	v_med3_f32 v36, v36, s76, v141
	v_med3_f32 v37, v37, s76, v141
	v_cvt_pk_fp8_f32 v34, v40, v41 op_sel:[0,0,1]
	v_cvt_pk_fp8_f32 v35, v36, v37 op_sel:[0,0,1]
	v_exp_f32_e64 v36, -v26
	v_exp_f32_e64 v37, -v27
	v_add_u32_e32 v38, 0x90, v142
	v_mad_i64_i32 v[38:39], s[0:1], v38, s77, v[114:115]
	v_lshl_add_u64 v[38:39], v[38:39], 0, v[134:135]
	global_store_dwordx2 v[38:39], v[34:35], off
	v_pk_add_f32 v[34:35], v[36:37], 1.0 op_sel_hi:[1,0]
	v_exp_f32_e64 v28, -v28
	v_exp_f32_e64 v29, -v29
	v_pk_mul_f32 v[26:27], v[26:27], v[30:31]
	v_rcp_f32_e32 v30, v34
	v_rcp_f32_e32 v31, v35
	v_pk_add_f32 v[28:29], v[28:29], 1.0 op_sel_hi:[1,0]
	v_pk_mul_f32 v[16:17], v[12:13], v[16:17]
	v_rcp_f32_e32 v28, v28
	v_rcp_f32_e32 v29, v29
	v_pk_mul_f32 v[26:27], v[30:31], v[26:27]
	v_exp_f32_e64 v30, -v18
	v_exp_f32_e64 v31, -v19
	v_pk_mul_f32 v[28:29], v[28:29], v[32:33]
	v_exp_f32_e64 v32, -v20
	v_exp_f32_e64 v33, -v21
	v_pk_add_f32 v[30:31], v[30:31], 1.0 op_sel_hi:[1,0]
	v_pk_mul_f32 v[18:19], v[18:19], v[22:23]
	v_rcp_f32_e32 v30, v30
	v_rcp_f32_e32 v31, v31
	v_pk_add_f32 v[32:33], v[32:33], 1.0 op_sel_hi:[1,0]
	v_med3_f32 v22, v26, s76, v141
	v_rcp_f32_e32 v32, v32
	v_rcp_f32_e32 v33, v33
	v_pk_mul_f32 v[18:19], v[30:31], v[18:19]
	v_med3_f32 v23, v27, s76, v141
	v_med3_f32 v26, v18, s76, v141
	v_med3_f32 v27, v19, s76, v141
	v_mov_b32_e32 v18, 0
	v_mov_b32_e32 v19, 0
	v_cvt_pk_fp8_f32 v18, v22, v23
	v_cvt_pk_fp8_f32 v19, v26, v27
	v_pk_mul_f32 v[20:21], v[20:21], v[24:25]
	v_med3_f32 v24, v28, s76, v141
	v_pk_mul_f32 v[20:21], v[32:33], v[20:21]
	v_med3_f32 v25, v29, s76, v141
	v_med3_f32 v20, v20, s76, v141
	v_med3_f32 v21, v21, s76, v141
	v_cvt_pk_fp8_f32 v18, v24, v25 op_sel:[0,0,1]
	v_cvt_pk_fp8_f32 v19, v20, v21 op_sel:[0,0,1]
	v_exp_f32_e64 v20, -v10
	v_exp_f32_e64 v21, -v11
	v_add_u32_e32 v22, 0xa0, v142
	v_mad_i64_i32 v[22:23], s[0:1], v22, s77, v[114:115]
	v_lshl_add_u64 v[22:23], v[22:23], 0, v[134:135]
	global_store_dwordx2 v[22:23], v[18:19], off
	v_pk_add_f32 v[18:19], v[20:21], 1.0 op_sel_hi:[1,0]
	v_exp_f32_e64 v12, -v12
	v_exp_f32_e64 v13, -v13
	v_pk_mul_f32 v[10:11], v[10:11], v[14:15]
	v_rcp_f32_e32 v14, v18
	v_rcp_f32_e32 v15, v19
	v_pk_add_f32 v[12:13], v[12:13], 1.0 op_sel_hi:[1,0]
	v_pk_mul_f32 v[2:3], v[6:7], v[2:3]
	v_rcp_f32_e32 v12, v12
	v_rcp_f32_e32 v13, v13
	v_pk_mul_f32 v[10:11], v[14:15], v[10:11]
	v_exp_f32_e64 v14, -v6
	v_exp_f32_e64 v15, -v7
	v_pk_mul_f32 v[12:13], v[12:13], v[16:17]
	v_exp_f32_e64 v16, -v8
	v_exp_f32_e64 v17, -v9
	v_pk_add_f32 v[14:15], v[14:15], 1.0 op_sel_hi:[1,0]
	v_med3_f32 v6, v10, s76, v141
	v_rcp_f32_e32 v14, v14
	v_rcp_f32_e32 v15, v15
	v_pk_add_f32 v[16:17], v[16:17], 1.0 op_sel_hi:[1,0]
	v_med3_f32 v7, v11, s76, v141
	v_rcp_f32_e32 v16, v16
	v_rcp_f32_e32 v17, v17
	v_pk_mul_f32 v[2:3], v[14:15], v[2:3]
	v_pk_mul_f32 v[4:5], v[8:9], v[4:5]
	v_med3_f32 v10, v2, s76, v141
	v_med3_f32 v11, v3, s76, v141
	v_mov_b32_e32 v2, 0
	v_mov_b32_e32 v3, 0
	v_cvt_pk_fp8_f32 v2, v6, v7
	v_cvt_pk_fp8_f32 v3, v10, v11
	v_pk_mul_f32 v[4:5], v[16:17], v[4:5]
	v_med3_f32 v121, v124, s76, v141
	v_med3_f32 v122, v125, s76, v141
	v_med3_f32 v8, v12, s76, v141
	v_med3_f32 v9, v13, s76, v141
	v_med3_f32 v4, v4, s76, v141
	v_med3_f32 v5, v5, s76, v141
	v_cvt_pk_fp8_f32 v118, v121, v122 op_sel:[0,0,1]
	v_cvt_pk_fp8_f32 v2, v8, v9 op_sel:[0,0,1]
	v_cvt_pk_fp8_f32 v3, v4, v5 op_sel:[0,0,1]
	v_add_u32_e32 v4, 0xb0, v142
	v_mad_i64_i32 v[120:121], s[0:1], v142, s77, v[114:115]
	v_mad_i64_i32 v[4:5], s[0:1], v4, s77, v[114:115]
	v_lshl_add_u64 v[120:121], v[120:121], 0, v[134:135]
	v_lshl_add_u64 v[4:5], v[4:5], 0, v[134:135]
	s_andn2_b64 vcc, exec, s[4:5]
	s_mov_b64 s[0:1], -1
	global_store_dwordx2 v[120:121], v[118:119], off
	global_store_dwordx2 v[4:5], v[2:3], off
	s_cbranch_vccnz .LBB0_553
	s_andn2_b64 vcc, exec, s[8:9]
	v_mov_b64 v[4:5], 0
	s_cbranch_vccnz .LBB0_552
	s_barrier
	s_branch .LBB0_552

.LBB0_803:
	v_exp_f32_e64 v144, -v122
	v_exp_f32_e64 v145, -v123
	v_pk_mul_f32 v[128:129], v[124:125], v[128:129]
	v_exp_f32_e64 v124, -v124
	v_exp_f32_e64 v125, -v125
	v_pk_add_f32 v[144:145], v[144:145], 1.0 op_sel_hi:[1,0]
	v_pk_mul_f32 v[122:123], v[122:123], v[126:127]
	v_rcp_f32_e32 v126, v144
	v_rcp_f32_e32 v127, v145
	v_pk_add_f32 v[124:125], v[124:125], 1.0 op_sel_hi:[1,0]
	v_pk_mul_f32 v[112:113], v[108:109], v[112:113]
	v_rcp_f32_e32 v124, v124
	v_rcp_f32_e32 v125, v125
	v_pk_mul_f32 v[122:123], v[126:127], v[122:123]
	v_exp_f32_e64 v126, -v114
	v_exp_f32_e64 v127, -v115
	v_pk_mul_f32 v[124:125], v[124:125], v[128:129]
	v_exp_f32_e64 v128, -v116
	v_exp_f32_e64 v129, -v117
	v_pk_add_f32 v[126:127], v[126:127], 1.0 op_sel_hi:[1,0]
	v_pk_mul_f32 v[114:115], v[114:115], v[118:119]
	v_rcp_f32_e32 v126, v126
	v_rcp_f32_e32 v127, v127
	v_pk_add_f32 v[128:129], v[128:129], 1.0 op_sel_hi:[1,0]
	v_pk_mul_f32 v[116:117], v[116:117], v[120:121]
	v_rcp_f32_e32 v128, v128
	v_rcp_f32_e32 v129, v129
	v_pk_mul_f32 v[114:115], v[126:127], v[114:115]
	v_med3_f32 v119, v122, s82, v141
	v_med3_f32 v120, v123, s82, v141
	v_mov_b32_e32 v118, 0
	v_pk_mul_f32 v[116:117], v[128:129], v[116:117]
	v_med3_f32 v114, v114, s82, v141
	v_med3_f32 v115, v115, s82, v141
	v_cvt_pk_fp8_f32 v118, v119, v120
	v_mov_b32_e32 v119, 0
	v_cvt_pk_fp8_f32 v119, v114, v115
	v_med3_f32 v114, v116, s82, v141
	v_med3_f32 v115, v117, s82, v141
	v_exp_f32_e64 v116, -v106
	v_exp_f32_e64 v117, -v107
	v_exp_f32_e64 v108, -v108
	v_exp_f32_e64 v109, -v109
	v_pk_mul_f32 v[106:107], v[106:107], v[110:111]
	v_pk_add_f32 v[116:117], v[116:117], 1.0 op_sel_hi:[1,0]
	v_lshl_add_u32 v142, s38, 8, v137
	v_rcp_f32_e32 v110, v116
	v_rcp_f32_e32 v111, v117
	s_and_b64 vcc, exec, s[8:9]
	s_cbranch_vccz .Lepibar_2
	s_barrier
.Lepibar_2:
	v_pk_add_f32 v[108:109], v[108:109], 1.0 op_sel_hi:[1,0]
	v_lshl_or_b32 v134, s85, 7, v138
	v_rcp_f32_e32 v108, v108
	v_rcp_f32_e32 v109, v109
	v_pk_mul_f32 v[106:107], v[110:111], v[106:107]
	v_exp_f32_e64 v110, -v98
	v_exp_f32_e64 v111, -v99
	v_pk_mul_f32 v[108:109], v[108:109], v[112:113]
	v_exp_f32_e64 v112, -v100
	v_exp_f32_e64 v113, -v101
	v_pk_add_f32 v[110:111], v[110:111], 1.0 op_sel_hi:[1,0]
	v_pk_mul_f32 v[98:99], v[98:99], v[102:103]
	v_rcp_f32_e32 v110, v110
	v_rcp_f32_e32 v111, v111
	v_pk_add_f32 v[112:113], v[112:113], 1.0 op_sel_hi:[1,0]
	v_med3_f32 v102, v106, s82, v141
	v_rcp_f32_e32 v112, v112
	v_rcp_f32_e32 v113, v113
	v_pk_mul_f32 v[98:99], v[110:111], v[98:99]
	v_med3_f32 v103, v107, s82, v141
	v_med3_f32 v106, v98, s82, v141
	v_med3_f32 v107, v99, s82, v141
	v_mov_b32_e32 v98, 0
	v_mov_b32_e32 v99, 0
	v_cvt_pk_fp8_f32 v98, v102, v103
	v_cvt_pk_fp8_f32 v99, v106, v107
	v_pk_mul_f32 v[100:101], v[100:101], v[104:105]
	v_med3_f32 v104, v108, s82, v141
	v_pk_mul_f32 v[100:101], v[112:113], v[100:101]
	v_med3_f32 v105, v109, s82, v141
	v_med3_f32 v100, v100, s82, v141
	v_med3_f32 v101, v101, s82, v141
	v_cvt_pk_fp8_f32 v98, v104, v105 op_sel:[0,0,1]
	v_cvt_pk_fp8_f32 v99, v100, v101 op_sel:[0,0,1]
	v_exp_f32_e64 v100, -v90
	v_exp_f32_e64 v101, -v91
	v_cvt_pk_fp8_f32 v119, v114, v115 op_sel:[0,0,1]
	v_mov_b64_e32 v[114:115], s[18:19]
	v_or_b32_e32 v102, 16, v142
	v_ashrrev_i32_e32 v135, 31, v134
	v_mad_i64_i32 v[102:103], s[0:1], v102, s84, v[114:115]
	v_lshl_add_u64 v[102:103], v[102:103], 0, v[134:135]
	global_store_dwordx2 v[102:103], v[98:99], off
	v_pk_add_f32 v[98:99], v[100:101], 1.0 op_sel_hi:[1,0]
	v_pk_mul_f32 v[96:97], v[92:93], v[96:97]
	v_exp_f32_e64 v92, -v92
	v_exp_f32_e64 v93, -v93
	v_pk_mul_f32 v[90:91], v[90:91], v[94:95]
	v_rcp_f32_e32 v94, v98
	v_rcp_f32_e32 v95, v99
	v_pk_add_f32 v[92:93], v[92:93], 1.0 op_sel_hi:[1,0]
	v_pk_mul_f32 v[80:81], v[76:77], v[80:81]
	v_rcp_f32_e32 v92, v92
	v_rcp_f32_e32 v93, v93
	v_pk_mul_f32 v[90:91], v[94:95], v[90:91]
	v_exp_f32_e64 v94, -v82
	v_exp_f32_e64 v95, -v83
	v_pk_mul_f32 v[92:93], v[92:93], v[96:97]
	v_exp_f32_e64 v96, -v84
	v_exp_f32_e64 v97, -v85
	v_pk_add_f32 v[94:95], v[94:95], 1.0 op_sel_hi:[1,0]
	v_pk_mul_f32 v[82:83], v[82:83], v[86:87]
	v_rcp_f32_e32 v94, v94
	v_rcp_f32_e32 v95, v95
	v_pk_add_f32 v[96:97], v[96:97], 1.0 op_sel_hi:[1,0]
	v_med3_f32 v86, v90, s82, v141
	v_rcp_f32_e32 v96, v96
	v_rcp_f32_e32 v97, v97
	v_pk_mul_f32 v[82:83], v[94:95], v[82:83]
	v_med3_f32 v87, v91, s82, v141
	v_med3_f32 v90, v82, s82, v141
	v_med3_f32 v91, v83, s82, v141
	v_mov_b32_e32 v82, 0
	v_mov_b32_e32 v83, 0
	v_cvt_pk_fp8_f32 v82, v86, v87
	v_cvt_pk_fp8_f32 v83, v90, v91
	v_pk_mul_f32 v[84:85], v[84:85], v[88:89]
	v_med3_f32 v88, v92, s82, v141
	v_pk_mul_f32 v[84:85], v[96:97], v[84:85]
	v_med3_f32 v89, v93, s82, v141
	v_med3_f32 v84, v84, s82, v141
	v_med3_f32 v85, v85, s82, v141
	v_cvt_pk_fp8_f32 v82, v88, v89 op_sel:[0,0,1]
	v_cvt_pk_fp8_f32 v83, v84, v85 op_sel:[0,0,1]
	v_exp_f32_e64 v84, -v74
	v_exp_f32_e64 v85, -v75
	v_or_b32_e32 v86, 32, v142
	v_mad_i64_i32 v[86:87], s[0:1], v86, s84, v[114:115]
	v_lshl_add_u64 v[86:87], v[86:87], 0, v[134:135]
	global_store_dwordx2 v[86:87], v[82:83], off
	v_pk_add_f32 v[82:83], v[84:85], 1.0 op_sel_hi:[1,0]
	v_exp_f32_e64 v76, -v76
	v_exp_f32_e64 v77, -v77
	v_pk_mul_f32 v[74:75], v[74:75], v[78:79]
	v_rcp_f32_e32 v78, v82
	v_rcp_f32_e32 v79, v83
	v_pk_add_f32 v[76:77], v[76:77], 1.0 op_sel_hi:[1,0]
	v_pk_mul_f32 v[64:65], v[60:61], v[64:65]
	v_rcp_f32_e32 v76, v76
	v_rcp_f32_e32 v77, v77
	v_pk_mul_f32 v[74:75], v[78:79], v[74:75]
	v_exp_f32_e64 v78, -v66
	v_exp_f32_e64 v79, -v67
	v_pk_mul_f32 v[76:77], v[76:77], v[80:81]
	v_exp_f32_e64 v80, -v68
	v_exp_f32_e64 v81, -v69
	v_pk_add_f32 v[78:79], v[78:79], 1.0 op_sel_hi:[1,0]
	v_pk_mul_f32 v[66:67], v[66:67], v[70:71]
	v_rcp_f32_e32 v78, v78
	v_rcp_f32_e32 v79, v79
	v_pk_add_f32 v[80:81], v[80:81], 1.0 op_sel_hi:[1,0]
	v_med3_f32 v70, v74, s82, v141
	v_rcp_f32_e32 v80, v80
	v_rcp_f32_e32 v81, v81
	v_pk_mul_f32 v[66:67], v[78:79], v[66:67]
	v_med3_f32 v71, v75, s82, v141
	v_med3_f32 v74, v66, s82, v141
	v_med3_f32 v75, v67, s82, v141
	v_mov_b32_e32 v66, 0
	v_mov_b32_e32 v67, 0
	v_cvt_pk_fp8_f32 v66, v70, v71
	v_cvt_pk_fp8_f32 v67, v74, v75
	v_pk_mul_f32 v[68:69], v[68:69], v[72:73]
	v_med3_f32 v72, v76, s82, v141
	v_pk_mul_f32 v[68:69], v[80:81], v[68:69]
	v_med3_f32 v73, v77, s82, v141
	v_med3_f32 v68, v68, s82, v141
	v_med3_f32 v69, v69, s82, v141
	v_cvt_pk_fp8_f32 v66, v72, v73 op_sel:[0,0,1]
	v_cvt_pk_fp8_f32 v67, v68, v69 op_sel:[0,0,1]
	v_exp_f32_e64 v70, -v58
	v_exp_f32_e64 v71, -v59
	v_or_b32_e32 v68, 48, v142
	v_mad_i64_i32 v[68:69], s[0:1], v68, s84, v[114:115]
	v_lshl_add_u64 v[68:69], v[68:69], 0, v[134:135]
	global_store_dwordx2 v[68:69], v[66:67], off
	v_pk_add_f32 v[66:67], v[70:71], 1.0 op_sel_hi:[1,0]
	v_exp_f32_e64 v60, -v60
	v_exp_f32_e64 v61, -v61
	v_pk_mul_f32 v[58:59], v[58:59], v[62:63]
	v_rcp_f32_e32 v62, v66
	v_rcp_f32_e32 v63, v67
	v_pk_add_f32 v[60:61], v[60:61], 1.0 op_sel_hi:[1,0]
	v_add_u32_e32 v68, 0x80, v142
	v_rcp_f32_e32 v60, v60
	v_rcp_f32_e32 v61, v61
	v_pk_mul_f32 v[58:59], v[62:63], v[58:59]
	v_exp_f32_e64 v62, -v50
	v_exp_f32_e64 v63, -v51
	v_pk_mul_f32 v[60:61], v[60:61], v[64:65]
	v_exp_f32_e64 v64, -v52
	v_exp_f32_e64 v65, -v53
	v_pk_add_f32 v[62:63], v[62:63], 1.0 op_sel_hi:[1,0]
	v_pk_mul_f32 v[50:51], v[50:51], v[54:55]
	v_rcp_f32_e32 v62, v62
	v_rcp_f32_e32 v63, v63
	v_pk_add_f32 v[64:65], v[64:65], 1.0 op_sel_hi:[1,0]
	v_med3_f32 v54, v58, s82, v141
	v_rcp_f32_e32 v64, v64
	v_rcp_f32_e32 v65, v65
	v_pk_mul_f32 v[50:51], v[62:63], v[50:51]
	v_med3_f32 v55, v59, s82, v141
	v_med3_f32 v58, v50, s82, v141
	v_med3_f32 v59, v51, s82, v141
	v_mov_b32_e32 v50, 0
	v_mov_b32_e32 v51, 0
	v_cvt_pk_fp8_f32 v50, v54, v55
	v_cvt_pk_fp8_f32 v51, v58, v59
	v_pk_mul_f32 v[52:53], v[52:53], v[56:57]
	v_med3_f32 v56, v60, s82, v141
	v_pk_mul_f32 v[52:53], v[64:65], v[52:53]
	v_med3_f32 v57, v61, s82, v141
	v_med3_f32 v52, v52, s82, v141
	v_med3_f32 v53, v53, s82, v141
	v_cvt_pk_fp8_f32 v50, v56, v57 op_sel:[0,0,1]
	v_cvt_pk_fp8_f32 v51, v52, v53 op_sel:[0,0,1]
	v_exp_f32_e64 v52, -v42
	v_exp_f32_e64 v53, -v43
	v_mad_i64_i32 v[54:55], s[0:1], v68, s84, v[114:115]
	v_lshl_add_u64 v[54:55], v[54:55], 0, v[134:135]
	global_store_dwordx2 v[54:55], v[50:51], off
	v_pk_add_f32 v[50:51], v[52:53], 1.0 op_sel_hi:[1,0]
	v_pk_mul_f32 v[48:49], v[44:45], v[48:49]
	v_exp_f32_e64 v44, -v44
	v_exp_f32_e64 v45, -v45
	v_pk_mul_f32 v[42:43], v[42:43], v[46:47]
	v_rcp_f32_e32 v46, v50
	v_rcp_f32_e32 v47, v51
	v_pk_add_f32 v[44:45], v[44:45], 1.0 op_sel_hi:[1,0]
	v_pk_mul_f32 v[32:33], v[28:29], v[32:33]
	v_rcp_f32_e32 v44, v44
	v_rcp_f32_e32 v45, v45
	v_pk_mul_f32 v[42:43], v[46:47], v[42:43]
	v_exp_f32_e64 v46, -v34
	v_exp_f32_e64 v47, -v35
	v_pk_mul_f32 v[44:45], v[44:45], v[48:49]
	v_exp_f32_e64 v48, -v36
	v_exp_f32_e64 v49, -v37
	v_pk_add_f32 v[46:47], v[46:47], 1.0 op_sel_hi:[1,0]
	v_pk_mul_f32 v[34:35], v[34:35], v[38:39]
	v_rcp_f32_e32 v46, v46
	v_rcp_f32_e32 v47, v47
	v_pk_add_f32 v[48:49], v[48:49], 1.0 op_sel_hi:[1,0]
	v_med3_f32 v38, v42, s82, v141
	v_rcp_f32_e32 v48, v48
	v_rcp_f32_e32 v49, v49
	v_pk_mul_f32 v[34:35], v[46:47], v[34:35]
	v_med3_f32 v39, v43, s82, v141
	v_med3_f32 v42, v34, s82, v141
	v_med3_f32 v43, v35, s82, v141
	v_mov_b32_e32 v34, 0
	v_mov_b32_e32 v35, 0
	v_cvt_pk_fp8_f32 v34, v38, v39
	v_cvt_pk_fp8_f32 v35, v42, v43
	v_pk_mul_f32 v[36:37], v[36:37], v[40:41]
	v_med3_f32 v40, v44, s82, v141
	v_pk_mul_f32 v[36:37], v[48:49], v[36:37]
	v_med3_f32 v41, v45, s82, v141
	v_med3_f32 v36, v36, s82, v141
	v_med3_f32 v37, v37, s82, v141
	v_cvt_pk_fp8_f32 v34, v40, v41 op_sel:[0,0,1]
	v_cvt_pk_fp8_f32 v35, v36, v37 op_sel:[0,0,1]
	v_exp_f32_e64 v36, -v26
	v_exp_f32_e64 v37, -v27
	v_add_u32_e32 v38, 0x90, v142
	v_mad_i64_i32 v[38:39], s[0:1], v38, s84, v[114:115]
	v_lshl_add_u64 v[38:39], v[38:39], 0, v[134:135]
	global_store_dwordx2 v[38:39], v[34:35], off
	v_pk_add_f32 v[34:35], v[36:37], 1.0 op_sel_hi:[1,0]
	v_exp_f32_e64 v28, -v28
	v_exp_f32_e64 v29, -v29
	v_pk_mul_f32 v[26:27], v[26:27], v[30:31]
	v_rcp_f32_e32 v30, v34
	v_rcp_f32_e32 v31, v35
	v_pk_add_f32 v[28:29], v[28:29], 1.0 op_sel_hi:[1,0]
	v_pk_mul_f32 v[16:17], v[12:13], v[16:17]
	v_rcp_f32_e32 v28, v28
	v_rcp_f32_e32 v29, v29
	v_pk_mul_f32 v[26:27], v[30:31], v[26:27]
	v_exp_f32_e64 v30, -v18
	v_exp_f32_e64 v31, -v19
	v_pk_mul_f32 v[28:29], v[28:29], v[32:33]
	v_exp_f32_e64 v32, -v20
	v_exp_f32_e64 v33, -v21
	v_pk_add_f32 v[30:31], v[30:31], 1.0 op_sel_hi:[1,0]
	v_pk_mul_f32 v[18:19], v[18:19], v[22:23]
	v_rcp_f32_e32 v30, v30
	v_rcp_f32_e32 v31, v31
	v_pk_add_f32 v[32:33], v[32:33], 1.0 op_sel_hi:[1,0]
	v_med3_f32 v22, v26, s82, v141
	v_rcp_f32_e32 v32, v32
	v_rcp_f32_e32 v33, v33
	v_pk_mul_f32 v[18:19], v[30:31], v[18:19]
	v_med3_f32 v23, v27, s82, v141
	v_med3_f32 v26, v18, s82, v141
	v_med3_f32 v27, v19, s82, v141
	v_mov_b32_e32 v18, 0
	v_mov_b32_e32 v19, 0
	v_cvt_pk_fp8_f32 v18, v22, v23
	v_cvt_pk_fp8_f32 v19, v26, v27
	v_pk_mul_f32 v[20:21], v[20:21], v[24:25]
	v_med3_f32 v24, v28, s82, v141
	v_pk_mul_f32 v[20:21], v[32:33], v[20:21]
	v_med3_f32 v25, v29, s82, v141
	v_med3_f32 v20, v20, s82, v141
	v_med3_f32 v21, v21, s82, v141
	v_cvt_pk_fp8_f32 v18, v24, v25 op_sel:[0,0,1]
	v_cvt_pk_fp8_f32 v19, v20, v21 op_sel:[0,0,1]
	v_exp_f32_e64 v20, -v10
	v_exp_f32_e64 v21, -v11
	v_add_u32_e32 v22, 0xa0, v142
	v_mad_i64_i32 v[22:23], s[0:1], v22, s84, v[114:115]
	v_lshl_add_u64 v[22:23], v[22:23], 0, v[134:135]
	global_store_dwordx2 v[22:23], v[18:19], off
	v_pk_add_f32 v[18:19], v[20:21], 1.0 op_sel_hi:[1,0]
	v_exp_f32_e64 v12, -v12
	v_exp_f32_e64 v13, -v13
	v_pk_mul_f32 v[10:11], v[10:11], v[14:15]
	v_rcp_f32_e32 v14, v18
	v_rcp_f32_e32 v15, v19
	v_pk_add_f32 v[12:13], v[12:13], 1.0 op_sel_hi:[1,0]
	v_pk_mul_f32 v[2:3], v[6:7], v[2:3]
	v_rcp_f32_e32 v12, v12
	v_rcp_f32_e32 v13, v13
	v_pk_mul_f32 v[10:11], v[14:15], v[10:11]
	v_exp_f32_e64 v14, -v6
	v_exp_f32_e64 v15, -v7
	v_pk_mul_f32 v[12:13], v[12:13], v[16:17]
	v_exp_f32_e64 v16, -v8
	v_exp_f32_e64 v17, -v9
	v_pk_add_f32 v[14:15], v[14:15], 1.0 op_sel_hi:[1,0]
	v_med3_f32 v6, v10, s82, v141
	v_rcp_f32_e32 v14, v14
	v_rcp_f32_e32 v15, v15
	v_pk_add_f32 v[16:17], v[16:17], 1.0 op_sel_hi:[1,0]
	v_med3_f32 v7, v11, s82, v141
	v_rcp_f32_e32 v16, v16
	v_rcp_f32_e32 v17, v17
	v_pk_mul_f32 v[2:3], v[14:15], v[2:3]
	v_pk_mul_f32 v[4:5], v[8:9], v[4:5]
	v_med3_f32 v10, v2, s82, v141
	v_med3_f32 v11, v3, s82, v141
	v_mov_b32_e32 v2, 0
	v_mov_b32_e32 v3, 0
	v_cvt_pk_fp8_f32 v2, v6, v7
	v_cvt_pk_fp8_f32 v3, v10, v11
	v_pk_mul_f32 v[4:5], v[16:17], v[4:5]
	v_med3_f32 v121, v124, s82, v141
	v_med3_f32 v122, v125, s82, v141
	v_med3_f32 v8, v12, s82, v141
	v_med3_f32 v9, v13, s82, v141
	v_med3_f32 v4, v4, s82, v141
	v_med3_f32 v5, v5, s82, v141
	v_cvt_pk_fp8_f32 v118, v121, v122 op_sel:[0,0,1]
	v_cvt_pk_fp8_f32 v2, v8, v9 op_sel:[0,0,1]
	v_cvt_pk_fp8_f32 v3, v4, v5 op_sel:[0,0,1]
	v_add_u32_e32 v4, 0xb0, v142
	v_mad_i64_i32 v[120:121], s[0:1], v142, s84, v[114:115]
	v_mad_i64_i32 v[4:5], s[0:1], v4, s84, v[114:115]
	v_lshl_add_u64 v[120:121], v[120:121], 0, v[134:135]
	v_lshl_add_u64 v[4:5], v[4:5], 0, v[134:135]
	s_andn2_b64 vcc, exec, s[4:5]
	s_mov_b64 s[0:1], -1
	global_store_dwordx2 v[120:121], v[118:119], off
	global_store_dwordx2 v[4:5], v[2:3], off
	s_cbranch_vccnz .LBB0_796
	s_andn2_b64 vcc, exec, s[6:7]
	v_mov_b64 v[4:5], 0
	s_cbranch_vccnz .LBB0_795
	s_barrier
	s_branch .LBB0_795

.LBB0_1427:
	v_exp_f32_e64 v144, -v122
	v_exp_f32_e64 v145, -v123
	v_pk_mul_f32 v[128:129], v[124:125], v[128:129]
	v_exp_f32_e64 v124, -v124
	v_exp_f32_e64 v125, -v125
	v_pk_add_f32 v[144:145], v[144:145], 1.0 op_sel_hi:[1,0]
	v_pk_mul_f32 v[122:123], v[122:123], v[126:127]
	v_rcp_f32_e32 v126, v144
	v_rcp_f32_e32 v127, v145
	v_pk_add_f32 v[124:125], v[124:125], 1.0 op_sel_hi:[1,0]
	v_pk_mul_f32 v[112:113], v[108:109], v[112:113]
	v_rcp_f32_e32 v124, v124
	v_rcp_f32_e32 v125, v125
	v_pk_mul_f32 v[122:123], v[126:127], v[122:123]
	v_exp_f32_e64 v126, -v114
	v_exp_f32_e64 v127, -v115
	v_pk_mul_f32 v[124:125], v[124:125], v[128:129]
	v_exp_f32_e64 v128, -v116
	v_exp_f32_e64 v129, -v117
	v_pk_add_f32 v[126:127], v[126:127], 1.0 op_sel_hi:[1,0]
	v_pk_mul_f32 v[114:115], v[114:115], v[118:119]
	v_rcp_f32_e32 v126, v126
	v_rcp_f32_e32 v127, v127
	v_pk_add_f32 v[128:129], v[128:129], 1.0 op_sel_hi:[1,0]
	v_pk_mul_f32 v[116:117], v[116:117], v[120:121]
	v_rcp_f32_e32 v128, v128
	v_rcp_f32_e32 v129, v129
	v_pk_mul_f32 v[114:115], v[126:127], v[114:115]
	v_med3_f32 v119, v122, s61, v141
	v_med3_f32 v120, v123, s61, v141
	v_mov_b32_e32 v118, 0
	v_pk_mul_f32 v[116:117], v[128:129], v[116:117]
	v_med3_f32 v114, v114, s61, v141
	v_med3_f32 v115, v115, s61, v141
	v_cvt_pk_fp8_f32 v118, v119, v120
	v_mov_b32_e32 v119, 0
	v_cvt_pk_fp8_f32 v119, v114, v115
	v_med3_f32 v114, v116, s61, v141
	v_med3_f32 v115, v117, s61, v141
	v_exp_f32_e64 v116, -v106
	v_exp_f32_e64 v117, -v107
	v_exp_f32_e64 v108, -v108
	v_exp_f32_e64 v109, -v109
	v_pk_mul_f32 v[106:107], v[106:107], v[110:111]
	v_pk_add_f32 v[116:117], v[116:117], 1.0 op_sel_hi:[1,0]
	v_lshl_add_u32 v142, s26, 8, v137
	v_rcp_f32_e32 v110, v116
	v_rcp_f32_e32 v111, v117
	s_and_b64 vcc, exec, s[8:9]
	s_cbranch_vccz .Lepibar_3
	s_barrier
.Lepibar_3:
	v_pk_add_f32 v[108:109], v[108:109], 1.0 op_sel_hi:[1,0]
	v_lshl_or_b32 v134, s63, 7, v138
	v_rcp_f32_e32 v108, v108
	v_rcp_f32_e32 v109, v109
	v_pk_mul_f32 v[106:107], v[110:111], v[106:107]
	v_exp_f32_e64 v110, -v98
	v_exp_f32_e64 v111, -v99
	v_pk_mul_f32 v[108:109], v[108:109], v[112:113]
	v_exp_f32_e64 v112, -v100
	v_exp_f32_e64 v113, -v101
	v_pk_add_f32 v[110:111], v[110:111], 1.0 op_sel_hi:[1,0]
	v_pk_mul_f32 v[98:99], v[98:99], v[102:103]
	v_rcp_f32_e32 v110, v110
	v_rcp_f32_e32 v111, v111
	v_pk_add_f32 v[112:113], v[112:113], 1.0 op_sel_hi:[1,0]
	v_med3_f32 v102, v106, s61, v141
	v_rcp_f32_e32 v112, v112
	v_rcp_f32_e32 v113, v113
	v_pk_mul_f32 v[98:99], v[110:111], v[98:99]
	v_med3_f32 v103, v107, s61, v141
	v_med3_f32 v106, v98, s61, v141
	v_med3_f32 v107, v99, s61, v141
	v_mov_b32_e32 v98, 0
	v_mov_b32_e32 v99, 0
	v_cvt_pk_fp8_f32 v98, v102, v103
	v_cvt_pk_fp8_f32 v99, v106, v107
	v_pk_mul_f32 v[100:101], v[100:101], v[104:105]
	v_med3_f32 v104, v108, s61, v141
	v_pk_mul_f32 v[100:101], v[112:113], v[100:101]
	v_med3_f32 v105, v109, s61, v141
	v_med3_f32 v100, v100, s61, v141
	v_med3_f32 v101, v101, s61, v141
	v_cvt_pk_fp8_f32 v98, v104, v105 op_sel:[0,0,1]
	v_cvt_pk_fp8_f32 v99, v100, v101 op_sel:[0,0,1]
	v_exp_f32_e64 v100, -v90
	v_exp_f32_e64 v101, -v91
	v_cvt_pk_fp8_f32 v119, v114, v115 op_sel:[0,0,1]
	v_mov_b64_e32 v[114:115], s[18:19]
	v_or_b32_e32 v102, 16, v142
	v_ashrrev_i32_e32 v135, 31, v134
	v_mad_i64_i32 v[102:103], s[0:1], v102, s62, v[114:115]
	v_lshl_add_u64 v[102:103], v[102:103], 0, v[134:135]
	global_store_dwordx2 v[102:103], v[98:99], off
	v_pk_add_f32 v[98:99], v[100:101], 1.0 op_sel_hi:[1,0]
	v_pk_mul_f32 v[96:97], v[92:93], v[96:97]
	v_exp_f32_e64 v92, -v92
	v_exp_f32_e64 v93, -v93
	v_pk_mul_f32 v[90:91], v[90:91], v[94:95]
	v_rcp_f32_e32 v94, v98
	v_rcp_f32_e32 v95, v99
	v_pk_add_f32 v[92:93], v[92:93], 1.0 op_sel_hi:[1,0]
	v_pk_mul_f32 v[80:81], v[76:77], v[80:81]
	v_rcp_f32_e32 v92, v92
	v_rcp_f32_e32 v93, v93
	v_pk_mul_f32 v[90:91], v[94:95], v[90:91]
	v_exp_f32_e64 v94, -v82
	v_exp_f32_e64 v95, -v83
	v_pk_mul_f32 v[92:93], v[92:93], v[96:97]
	v_exp_f32_e64 v96, -v84
	v_exp_f32_e64 v97, -v85
	v_pk_add_f32 v[94:95], v[94:95], 1.0 op_sel_hi:[1,0]
	v_pk_mul_f32 v[82:83], v[82:83], v[86:87]
	v_rcp_f32_e32 v94, v94
	v_rcp_f32_e32 v95, v95
	v_pk_add_f32 v[96:97], v[96:97], 1.0 op_sel_hi:[1,0]
	v_med3_f32 v86, v90, s61, v141
	v_rcp_f32_e32 v96, v96
	v_rcp_f32_e32 v97, v97
	v_pk_mul_f32 v[82:83], v[94:95], v[82:83]
	v_med3_f32 v87, v91, s61, v141
	v_med3_f32 v90, v82, s61, v141
	v_med3_f32 v91, v83, s61, v141
	v_mov_b32_e32 v82, 0
	v_mov_b32_e32 v83, 0
	v_cvt_pk_fp8_f32 v82, v86, v87
	v_cvt_pk_fp8_f32 v83, v90, v91
	v_pk_mul_f32 v[84:85], v[84:85], v[88:89]
	v_med3_f32 v88, v92, s61, v141
	v_pk_mul_f32 v[84:85], v[96:97], v[84:85]
	v_med3_f32 v89, v93, s61, v141
	v_med3_f32 v84, v84, s61, v141
	v_med3_f32 v85, v85, s61, v141
	v_cvt_pk_fp8_f32 v82, v88, v89 op_sel:[0,0,1]
	v_cvt_pk_fp8_f32 v83, v84, v85 op_sel:[0,0,1]
	v_exp_f32_e64 v84, -v74
	v_exp_f32_e64 v85, -v75
	v_or_b32_e32 v86, 32, v142
	v_mad_i64_i32 v[86:87], s[0:1], v86, s62, v[114:115]
	v_lshl_add_u64 v[86:87], v[86:87], 0, v[134:135]
	global_store_dwordx2 v[86:87], v[82:83], off
	v_pk_add_f32 v[82:83], v[84:85], 1.0 op_sel_hi:[1,0]
	v_exp_f32_e64 v76, -v76
	v_exp_f32_e64 v77, -v77
	v_pk_mul_f32 v[74:75], v[74:75], v[78:79]
	v_rcp_f32_e32 v78, v82
	v_rcp_f32_e32 v79, v83
	v_pk_add_f32 v[76:77], v[76:77], 1.0 op_sel_hi:[1,0]
	v_pk_mul_f32 v[64:65], v[60:61], v[64:65]
	v_rcp_f32_e32 v76, v76
	v_rcp_f32_e32 v77, v77
	v_pk_mul_f32 v[74:75], v[78:79], v[74:75]
	v_exp_f32_e64 v78, -v66
	v_exp_f32_e64 v79, -v67
	v_pk_mul_f32 v[76:77], v[76:77], v[80:81]
	v_exp_f32_e64 v80, -v68
	v_exp_f32_e64 v81, -v69
	v_pk_add_f32 v[78:79], v[78:79], 1.0 op_sel_hi:[1,0]
	v_pk_mul_f32 v[66:67], v[66:67], v[70:71]
	v_rcp_f32_e32 v78, v78
	v_rcp_f32_e32 v79, v79
	v_pk_add_f32 v[80:81], v[80:81], 1.0 op_sel_hi:[1,0]
	v_med3_f32 v70, v74, s61, v141
	v_rcp_f32_e32 v80, v80
	v_rcp_f32_e32 v81, v81
	v_pk_mul_f32 v[66:67], v[78:79], v[66:67]
	v_med3_f32 v71, v75, s61, v141
	v_med3_f32 v74, v66, s61, v141
	v_med3_f32 v75, v67, s61, v141
	v_mov_b32_e32 v66, 0
	v_mov_b32_e32 v67, 0
	v_cvt_pk_fp8_f32 v66, v70, v71
	v_cvt_pk_fp8_f32 v67, v74, v75
	v_pk_mul_f32 v[68:69], v[68:69], v[72:73]
	v_med3_f32 v72, v76, s61, v141
	v_pk_mul_f32 v[68:69], v[80:81], v[68:69]
	v_med3_f32 v73, v77, s61, v141
	v_med3_f32 v68, v68, s61, v141
	v_med3_f32 v69, v69, s61, v141
	v_cvt_pk_fp8_f32 v66, v72, v73 op_sel:[0,0,1]
	v_cvt_pk_fp8_f32 v67, v68, v69 op_sel:[0,0,1]
	v_exp_f32_e64 v70, -v58
	v_exp_f32_e64 v71, -v59
	v_or_b32_e32 v68, 48, v142
	v_mad_i64_i32 v[68:69], s[0:1], v68, s62, v[114:115]
	v_lshl_add_u64 v[68:69], v[68:69], 0, v[134:135]
	global_store_dwordx2 v[68:69], v[66:67], off
	v_pk_add_f32 v[66:67], v[70:71], 1.0 op_sel_hi:[1,0]
	v_exp_f32_e64 v60, -v60
	v_exp_f32_e64 v61, -v61
	v_pk_mul_f32 v[58:59], v[58:59], v[62:63]
	v_rcp_f32_e32 v62, v66
	v_rcp_f32_e32 v63, v67
	v_pk_add_f32 v[60:61], v[60:61], 1.0 op_sel_hi:[1,0]
	v_add_u32_e32 v68, 0x80, v142
	v_rcp_f32_e32 v60, v60
	v_rcp_f32_e32 v61, v61
	v_pk_mul_f32 v[58:59], v[62:63], v[58:59]
	v_exp_f32_e64 v62, -v50
	v_exp_f32_e64 v63, -v51
	v_pk_mul_f32 v[60:61], v[60:61], v[64:65]
	v_exp_f32_e64 v64, -v52
	v_exp_f32_e64 v65, -v53
	v_pk_add_f32 v[62:63], v[62:63], 1.0 op_sel_hi:[1,0]
	v_pk_mul_f32 v[50:51], v[50:51], v[54:55]
	v_rcp_f32_e32 v62, v62
	v_rcp_f32_e32 v63, v63
	v_pk_add_f32 v[64:65], v[64:65], 1.0 op_sel_hi:[1,0]
	v_med3_f32 v54, v58, s61, v141
	v_rcp_f32_e32 v64, v64
	v_rcp_f32_e32 v65, v65
	v_pk_mul_f32 v[50:51], v[62:63], v[50:51]
	v_med3_f32 v55, v59, s61, v141
	v_med3_f32 v58, v50, s61, v141
	v_med3_f32 v59, v51, s61, v141
	v_mov_b32_e32 v50, 0
	v_mov_b32_e32 v51, 0
	v_cvt_pk_fp8_f32 v50, v54, v55
	v_cvt_pk_fp8_f32 v51, v58, v59
	v_pk_mul_f32 v[52:53], v[52:53], v[56:57]
	v_med3_f32 v56, v60, s61, v141
	v_pk_mul_f32 v[52:53], v[64:65], v[52:53]
	v_med3_f32 v57, v61, s61, v141
	v_med3_f32 v52, v52, s61, v141
	v_med3_f32 v53, v53, s61, v141
	v_cvt_pk_fp8_f32 v50, v56, v57 op_sel:[0,0,1]
	v_cvt_pk_fp8_f32 v51, v52, v53 op_sel:[0,0,1]
	v_exp_f32_e64 v52, -v42
	v_exp_f32_e64 v53, -v43
	v_mad_i64_i32 v[54:55], s[0:1], v68, s62, v[114:115]
	v_lshl_add_u64 v[54:55], v[54:55], 0, v[134:135]
	global_store_dwordx2 v[54:55], v[50:51], off
	v_pk_add_f32 v[50:51], v[52:53], 1.0 op_sel_hi:[1,0]
	v_pk_mul_f32 v[48:49], v[44:45], v[48:49]
	v_exp_f32_e64 v44, -v44
	v_exp_f32_e64 v45, -v45
	v_pk_mul_f32 v[42:43], v[42:43], v[46:47]
	v_rcp_f32_e32 v46, v50
	v_rcp_f32_e32 v47, v51
	v_pk_add_f32 v[44:45], v[44:45], 1.0 op_sel_hi:[1,0]
	v_pk_mul_f32 v[32:33], v[28:29], v[32:33]
	v_rcp_f32_e32 v44, v44
	v_rcp_f32_e32 v45, v45
	v_pk_mul_f32 v[42:43], v[46:47], v[42:43]
	v_exp_f32_e64 v46, -v34
	v_exp_f32_e64 v47, -v35
	v_pk_mul_f32 v[44:45], v[44:45], v[48:49]
	v_exp_f32_e64 v48, -v36
	v_exp_f32_e64 v49, -v37
	v_pk_add_f32 v[46:47], v[46:47], 1.0 op_sel_hi:[1,0]
	v_pk_mul_f32 v[34:35], v[34:35], v[38:39]
	v_rcp_f32_e32 v46, v46
	v_rcp_f32_e32 v47, v47
	v_pk_add_f32 v[48:49], v[48:49], 1.0 op_sel_hi:[1,0]
	v_med3_f32 v38, v42, s61, v141
	v_rcp_f32_e32 v48, v48
	v_rcp_f32_e32 v49, v49
	v_pk_mul_f32 v[34:35], v[46:47], v[34:35]
	v_med3_f32 v39, v43, s61, v141
	v_med3_f32 v42, v34, s61, v141
	v_med3_f32 v43, v35, s61, v141
	v_mov_b32_e32 v34, 0
	v_mov_b32_e32 v35, 0
	v_cvt_pk_fp8_f32 v34, v38, v39
	v_cvt_pk_fp8_f32 v35, v42, v43
	v_pk_mul_f32 v[36:37], v[36:37], v[40:41]
	v_med3_f32 v40, v44, s61, v141
	v_pk_mul_f32 v[36:37], v[48:49], v[36:37]
	v_med3_f32 v41, v45, s61, v141
	v_med3_f32 v36, v36, s61, v141
	v_med3_f32 v37, v37, s61, v141
	v_cvt_pk_fp8_f32 v34, v40, v41 op_sel:[0,0,1]
	v_cvt_pk_fp8_f32 v35, v36, v37 op_sel:[0,0,1]
	v_exp_f32_e64 v36, -v26
	v_exp_f32_e64 v37, -v27
	v_add_u32_e32 v38, 0x90, v142
	v_mad_i64_i32 v[38:39], s[0:1], v38, s62, v[114:115]
	v_lshl_add_u64 v[38:39], v[38:39], 0, v[134:135]
	global_store_dwordx2 v[38:39], v[34:35], off
	v_pk_add_f32 v[34:35], v[36:37], 1.0 op_sel_hi:[1,0]
	v_exp_f32_e64 v28, -v28
	v_exp_f32_e64 v29, -v29
	v_pk_mul_f32 v[26:27], v[26:27], v[30:31]
	v_rcp_f32_e32 v30, v34
	v_rcp_f32_e32 v31, v35
	v_pk_add_f32 v[28:29], v[28:29], 1.0 op_sel_hi:[1,0]
	v_pk_mul_f32 v[16:17], v[12:13], v[16:17]
	v_rcp_f32_e32 v28, v28
	v_rcp_f32_e32 v29, v29
	v_pk_mul_f32 v[26:27], v[30:31], v[26:27]
	v_exp_f32_e64 v30, -v18
	v_exp_f32_e64 v31, -v19
	v_pk_mul_f32 v[28:29], v[28:29], v[32:33]
	v_exp_f32_e64 v32, -v20
	v_exp_f32_e64 v33, -v21
	v_pk_add_f32 v[30:31], v[30:31], 1.0 op_sel_hi:[1,0]
	v_pk_mul_f32 v[18:19], v[18:19], v[22:23]
	v_rcp_f32_e32 v30, v30
	v_rcp_f32_e32 v31, v31
	v_pk_add_f32 v[32:33], v[32:33], 1.0 op_sel_hi:[1,0]
	v_med3_f32 v22, v26, s61, v141
	v_rcp_f32_e32 v32, v32
	v_rcp_f32_e32 v33, v33
	v_pk_mul_f32 v[18:19], v[30:31], v[18:19]
	v_med3_f32 v23, v27, s61, v141
	v_med3_f32 v26, v18, s61, v141
	v_med3_f32 v27, v19, s61, v141
	v_mov_b32_e32 v18, 0
	v_mov_b32_e32 v19, 0
	v_cvt_pk_fp8_f32 v18, v22, v23
	v_cvt_pk_fp8_f32 v19, v26, v27
	v_pk_mul_f32 v[20:21], v[20:21], v[24:25]
	v_med3_f32 v24, v28, s61, v141
	v_pk_mul_f32 v[20:21], v[32:33], v[20:21]
	v_med3_f32 v25, v29, s61, v141
	v_med3_f32 v20, v20, s61, v141
	v_med3_f32 v21, v21, s61, v141
	v_cvt_pk_fp8_f32 v18, v24, v25 op_sel:[0,0,1]
	v_cvt_pk_fp8_f32 v19, v20, v21 op_sel:[0,0,1]
	v_exp_f32_e64 v20, -v10
	v_exp_f32_e64 v21, -v11
	v_add_u32_e32 v22, 0xa0, v142
	v_mad_i64_i32 v[22:23], s[0:1], v22, s62, v[114:115]
	v_lshl_add_u64 v[22:23], v[22:23], 0, v[134:135]
	global_store_dwordx2 v[22:23], v[18:19], off
	v_pk_add_f32 v[18:19], v[20:21], 1.0 op_sel_hi:[1,0]
	v_exp_f32_e64 v12, -v12
	v_exp_f32_e64 v13, -v13
	v_pk_mul_f32 v[10:11], v[10:11], v[14:15]
	v_rcp_f32_e32 v14, v18
	v_rcp_f32_e32 v15, v19
	v_pk_add_f32 v[12:13], v[12:13], 1.0 op_sel_hi:[1,0]
	v_pk_mul_f32 v[2:3], v[6:7], v[2:3]
	v_rcp_f32_e32 v12, v12
	v_rcp_f32_e32 v13, v13
	v_pk_mul_f32 v[10:11], v[14:15], v[10:11]
	v_exp_f32_e64 v14, -v6
	v_exp_f32_e64 v15, -v7
	v_pk_mul_f32 v[12:13], v[12:13], v[16:17]
	v_exp_f32_e64 v16, -v8
	v_exp_f32_e64 v17, -v9
	v_pk_add_f32 v[14:15], v[14:15], 1.0 op_sel_hi:[1,0]
	v_med3_f32 v6, v10, s61, v141
	v_rcp_f32_e32 v14, v14
	v_rcp_f32_e32 v15, v15
	v_pk_add_f32 v[16:17], v[16:17], 1.0 op_sel_hi:[1,0]
	v_med3_f32 v7, v11, s61, v141
	v_rcp_f32_e32 v16, v16
	v_rcp_f32_e32 v17, v17
	v_pk_mul_f32 v[2:3], v[14:15], v[2:3]
	v_pk_mul_f32 v[4:5], v[8:9], v[4:5]
	v_med3_f32 v10, v2, s61, v141
	v_med3_f32 v11, v3, s61, v141
	v_mov_b32_e32 v2, 0
	v_mov_b32_e32 v3, 0
	v_cvt_pk_fp8_f32 v2, v6, v7
	v_cvt_pk_fp8_f32 v3, v10, v11
	v_pk_mul_f32 v[4:5], v[16:17], v[4:5]
	v_med3_f32 v121, v124, s61, v141
	v_med3_f32 v122, v125, s61, v141
	v_med3_f32 v8, v12, s61, v141
	v_med3_f32 v9, v13, s61, v141
	v_med3_f32 v4, v4, s61, v141
	v_med3_f32 v5, v5, s61, v141
	v_cvt_pk_fp8_f32 v118, v121, v122 op_sel:[0,0,1]
	v_cvt_pk_fp8_f32 v2, v8, v9 op_sel:[0,0,1]
	v_cvt_pk_fp8_f32 v3, v4, v5 op_sel:[0,0,1]
	v_add_u32_e32 v4, 0xb0, v142
	v_mad_i64_i32 v[120:121], s[0:1], v142, s62, v[114:115]
	v_mad_i64_i32 v[4:5], s[0:1], v4, s62, v[114:115]
	v_lshl_add_u64 v[120:121], v[120:121], 0, v[134:135]
	v_lshl_add_u64 v[4:5], v[4:5], 0, v[134:135]
	s_andn2_b64 vcc, exec, s[2:3]
	s_mov_b64 s[0:1], -1
	global_store_dwordx2 v[120:121], v[118:119], off
	global_store_dwordx2 v[4:5], v[2:3], off
	s_cbranch_vccnz .LBB0_1420
	s_andn2_b64 vcc, exec, s[6:7]
	v_mov_b64 v[4:5], 0
	s_cbranch_vccnz .LBB0_1419
	s_barrier
	s_branch .LBB0_1419
